# M3 ssmy units: the four group-norm weight pieces ride in the unit's first load batch, kernarg pointer fetched once per phase; no loads or waits left in the ssmy epilogue
# baseline (speedup 1.0000x reference)
.LBB0_906:
	s_cmp_lt_i32 s88, 5
	s_cselect_b64 s[0:1], -1, 0
	s_cmp_gt_i32 s89, 4
	s_cselect_b64 s[2:3], -1, 0
	s_and_b64 s[0:1], s[0:1], s[2:3]
	s_andn2_b64 vcc, exec, s[0:1]
	s_cbranch_vccnz .LBB0_979
	v_readlane_b32 s0, v254, 0
	v_mbcnt_lo_u32_b32 v0, -1, 0
	s_andn2_b32 s0, s0, 63
	v_mbcnt_hi_u32_b32 v32, -1, v0
	v_or_b32_e32 v30, s0, v32
	s_mov_b32 s22, s90
	v_readlane_b32 s2, v254, 3
	s_mov_b64 s[0:1], s[92:93]
	v_readlane_b32 s23, v254, 4
	v_mov_b32_e32 v31, 0
	s_load_dwordx2 s[4:5], s[0:1], 0xe8
	s_load_dwordx2 s[38:39], s[0:1], 0x68
	s_load_dwordx2 s[40:41], s[0:1], 0x98
	s_mov_b32 s7, 0
	v_mov_b32_e32 v25, 0
	s_cmpk_gt_i32 s23, 0x3ff
	v_xor_b32_e32 v34, 16, v32
	v_and_b32_e32 v35, 64, v32
	v_xor_b32_e32 v33, 32, v32
	s_cbranch_scc1 .LBB0_920
	s_waitcnt lgkmcnt(0)
	s_add_u32 s24, s4, 0x10000000
	s_addc_u32 s25, s5, 0
	v_add_u32_e32 v0, 64, v35
	s_add_u32 s26, s4, 0x16100000
	v_cmp_lt_i32_e32 vcc, v34, v0
	s_addc_u32 s27, s5, 0
	s_add_u32 s8, s4, 0xb00000
	v_cndmask_b32_e32 v1, v32, v34, vcc
	v_cmp_lt_i32_e32 vcc, v33, v0
	s_addc_u32 s9, s5, 0
	v_lshlrev_b32_e32 v36, 2, v1
	v_cndmask_b32_e32 v0, v32, v33, vcc
	v_lshlrev_b32_e32 v37, 2, v0
	s_mov_b64 s[10:11], 0x10000
	s_mov_b64 s[12:13], 0x10400
	s_mov_b64 s[14:15], 0x14000
	s_movk_i32 s28, 0x1c00
	v_mov_b64_e32 v[26:27], s[4:5]
	s_mov_b64 s[16:17], 0x2e00c00
	s_mov_b32 s29, 0x2e00000
	s_mov_b32 s30, 0xc000
	v_mov_b32_e32 v38, 0x358637bd
	s_mov_b32 s31, 0x800000
	s_mov_b32 s33, s23
	s_branch .LBB0_910

.LBB0_929:
	s_or_b64 exec, exec, s[10:11]
	s_nop 0
	s_lshl_b32 s10, s13, 6
	v_lshrrev_b32_e32 v2, 1, v14
	v_mad_i64_i32 v[0:1], s[2:3], v12, s17, v[8:9]
	s_ashr_i32 s11, s10, 31
	v_and_b32_e32 v28, 24, v2
	v_bitop3_b32 v20, v10, v16, s16 bitop3:0x6c
	v_bitop3_b32 v19, v10, v18, s16 bitop3:0x6c
	v_lshl_add_u64 v[0:1], s[10:11], 1, v[0:1]
	v_lshlrev_b32_e32 v10, 1, v28
	v_lshl_add_u64 v[0:1], v[0:1], 0, v[10:11]
	v_add_co_u32_e64 v48, s[2:3], s18, v0
	s_nop 0
	v_addc_co_u32_e64 v49, s[2:3], 0, v1, s[2:3]
	v_lshl_add_u64 v[42:43], v[0:1], 0, s[6:7]
	v_or_b32_e32 v158, s10, v28
	v_lshlrev_b32_e32 v158, 2, v158
	global_load_dwordx4 v[142:145], v158, s[40:41] offset:0
	global_load_dwordx4 v[146:149], v158, s[40:41] offset:16
	global_load_dwordx4 v[150:153], v158, s[40:41] offset:128
	global_load_dwordx4 v[154:157], v158, s[40:41] offset:144
	global_load_dwordx4 v[44:47], v[48:49], off offset:1536
	global_load_dwordx4 v[0:3], v[42:43], off offset:64
	v_lshl_add_u32 v4, s20, 14, v31
	v_lshlrev_b32_e32 v15, 1, v15
	v_and_b32_e32 v14, 3, v14
	v_lshl_add_u32 v10, v27, 8, v4
	v_and_or_b32 v15, v15, 24, v14
	s_waitcnt vmcnt(0) lgkmcnt(0)
	s_barrier
	v_lshlrev_b32_e32 v36, 16, v118
	v_and_b32_e32 v37, 0xffff0000, v118
	v_lshlrev_b32_e32 v32, 16, v116
	v_and_b32_e32 v33, 0xffff0000, v116
	v_lshlrev_b32_e32 v34, 16, v117
	v_and_b32_e32 v35, 0xffff0000, v117
	v_lshlrev_b32_e32 v38, 16, v119
	v_and_b32_e32 v39, 0xffff0000, v119
	v_lshlrev_b32_e32 v40, 16, v120
	v_and_b32_e32 v41, 0xffff0000, v120
	v_lshlrev_b32_e32 v29, 4, v14
	v_add_u32_e32 v14, v10, v20
	v_lshl_add_u32 v64, v15, 8, v4
	v_xad_u32 v20, v29, v16, v64
	ds_read_b128 v[48:51], v14 offset:32768
	ds_read_b128 v[52:55], v20
	v_lshlrev_b32_e32 v42, 16, v121
	v_and_b32_e32 v43, 0xffff0000, v121
	v_or_b32_e32 v5, 4, v15
	v_lshlrev_b32_e32 v14, 4, v5
	v_and_b32_e32 v65, 0x70, v14
	v_lshl_add_u32 v66, v5, 8, v4
	v_xad_u32 v5, v65, v16, v66
	ds_read_b128 v[56:59], v5
	s_waitcnt lgkmcnt(0)
	v_mfma_f32_16x16x32_bf16 v[32:35], v[52:55], v[48:51], v[32:35]
	ds_read_b128 v[52:55], v20 offset:8192
	v_or_b32_e32 v5, 36, v15
	v_lshlrev_b32_e32 v14, 4, v5
	v_and_b32_e32 v67, 0x70, v14
	v_lshl_add_u32 v68, v5, 8, v4
	v_xad_u32 v4, v67, v16, v68
	ds_read_b128 v[60:63], v4
	v_add_u32_e32 v14, v10, v19
	v_and_b32_e32 v5, 0xffff0000, v122
	s_waitcnt lgkmcnt(1)
	v_mfma_f32_16x16x32_bf16 v[40:43], v[52:55], v[48:51], v[40:43]
	ds_read_b128 v[52:55], v14 offset:32768
	v_lshlrev_b32_e32 v4, 16, v122
	v_lshlrev_b32_e32 v6, 16, v123
	v_and_b32_e32 v7, 0xffff0000, v123
	v_xad_u32 v14, v29, v18, v64
	v_mfma_f32_16x16x32_bf16 v[36:39], v[56:59], v[48:51], v[36:39]
	v_cmp_gt_u32_e64 s[2:3], 16, v26
	s_waitcnt lgkmcnt(1)
	v_mfma_f32_16x16x32_bf16 v[4:7], v[60:63], v[48:51], v[4:7]
	ds_read_b128 v[48:51], v14
	ds_read_b128 v[56:59], v14 offset:8192
	v_xad_u32 v14, v65, v18, v66
	s_waitcnt lgkmcnt(1)
	v_mfma_f32_16x16x32_bf16 v[32:35], v[48:51], v[52:55], v[32:35]
	ds_read_b128 v[48:51], v14
	v_xad_u32 v14, v67, v18, v68
	ds_read_b128 v[18:21], v14
	v_or_b32_e32 v14, 0x80, v16
	v_xad_u32 v15, v29, v14, v64
	s_waitcnt lgkmcnt(1)
	v_mfma_f32_16x16x32_bf16 v[36:39], v[48:51], v[52:55], v[36:39]
	ds_read_b128 v[48:51], v15
	s_waitcnt lgkmcnt(1)
	v_mfma_f32_16x16x32_bf16 v[4:7], v[18:21], v[52:55], v[4:7]
	v_xad_u32 v18, v17, v14, v10
	ds_read_b128 v[18:21], v18 offset:32768
	s_waitcnt lgkmcnt(0)
	v_mfma_f32_16x16x32_bf16 v[32:35], v[48:51], v[18:21], v[32:35]
	v_xad_u32 v48, v65, v14, v66
	v_xad_u32 v14, v67, v14, v68
	v_mfma_f32_16x16x32_bf16 v[40:43], v[56:59], v[52:55], v[40:43]
	ds_read_b128 v[48:51], v48
	ds_read_b128 v[52:55], v15 offset:8192
	s_waitcnt vmcnt(1)
	v_lshlrev_b32_e32 v56, 16, v44
	s_waitcnt lgkmcnt(1)
	v_mfma_f32_16x16x32_bf16 v[36:39], v[48:51], v[18:21], v[36:39]
	ds_read_b128 v[48:51], v14
	v_and_b32_e32 v57, 0xffff0000, v44
	s_waitcnt lgkmcnt(1)
	v_mfma_f32_16x16x32_bf16 v[40:43], v[52:55], v[18:21], v[40:43]
	v_or_b32_e32 v52, 0xc0, v16
	v_xad_u32 v10, v17, v52, v10
	ds_read_b128 v[14:17], v10 offset:32768
	v_xad_u32 v10, v29, v52, v64
	s_waitcnt lgkmcnt(1)
	v_mfma_f32_16x16x32_bf16 v[4:7], v[48:51], v[18:21], v[4:7]
	ds_read_b128 v[18:21], v10
	ds_read_b128 v[48:51], v10 offset:8192
	v_xad_u32 v10, v65, v52, v66
	v_mul_f32_e32 v29, 0xbfb8aa3b, v57
	s_waitcnt lgkmcnt(1)
	v_mfma_f32_16x16x32_bf16 v[18:21], v[18:21], v[14:17], v[32:35]
	v_exp_f32_e32 v29, v29
	s_nop 1
	ds_read_b128 v[32:35], v10
	v_xad_u32 v10, v67, v52, v68
	ds_read_b128 v[52:55], v10
	v_mul_f32_e32 v10, 0xbfb8aa3b, v56
	v_exp_f32_e32 v10, v10
	s_waitcnt lgkmcnt(1)
	v_mfma_f32_16x16x32_bf16 v[32:35], v[32:35], v[14:17], v[36:39]
	v_add_f32_e32 v10, 1.0, v10
	v_rcp_f32_e32 v44, v10
	v_add_f32_e32 v10, 1.0, v29
	v_mfma_f32_16x16x32_bf16 v[36:39], v[48:51], v[14:17], v[40:43]
	v_lshlrev_b32_e32 v48, 16, v45
	v_and_b32_e32 v49, 0xffff0000, v45
	v_mul_f32_e32 v29, 0xbfb8aa3b, v48
	v_exp_f32_e32 v29, v29
	v_mul_f32_e32 v40, 0xbfb8aa3b, v49
	v_exp_f32_e32 v40, v40
	v_rcp_f32_e32 v45, v10
	v_add_f32_e32 v10, 1.0, v29
	v_rcp_f32_e32 v50, v10
	v_add_f32_e32 v10, 1.0, v40
	s_waitcnt lgkmcnt(0)
	v_mfma_f32_16x16x32_bf16 v[40:43], v[52:55], v[14:17], v[4:7]
	v_lshlrev_b32_e32 v14, 16, v46
	v_rcp_f32_e32 v51, v10
	v_and_b32_e32 v15, 0xffff0000, v46
	v_mul_f32_e32 v10, 0xbfb8aa3b, v14
	v_exp_f32_e32 v10, v10
	v_mul_f32_e32 v16, 0xbfb8aa3b, v15
	v_exp_f32_e32 v17, v16
	v_pk_mul_f32 v[4:5], v[44:45], v[56:57]
	v_add_f32_e32 v10, 1.0, v10
	v_pk_mul_f32 v[4:5], v[4:5], v[18:19]
	v_lshlrev_b32_e32 v18, 16, v47
	v_pk_mul_f32 v[6:7], v[50:51], v[48:49]
	v_rcp_f32_e32 v16, v10
	v_add_f32_e32 v10, 1.0, v17
	v_and_b32_e32 v19, 0xffff0000, v47
	v_mul_f32_e32 v17, 0xbfb8aa3b, v18
	v_pk_mul_f32 v[6:7], v[6:7], v[20:21]
	v_exp_f32_e32 v20, v17
	v_mul_f32_e32 v17, 0xbfb8aa3b, v19
	v_exp_f32_e32 v21, v17
	v_rcp_f32_e32 v17, v10
	v_add_f32_e32 v10, 1.0, v20
	v_rcp_f32_e32 v20, v10
	v_add_f32_e32 v10, 1.0, v21
	v_rcp_f32_e32 v21, v10
	v_pk_mul_f32 v[14:15], v[16:17], v[14:15]
	v_pk_mul_f32 v[44:45], v[4:5], v[4:5]
	v_pk_mul_f32 v[14:15], v[14:15], v[32:33]
	v_pk_mul_f32 v[16:17], v[20:21], v[18:19]
	s_waitcnt vmcnt(0)
	v_and_b32_e32 v19, 0xffff0000, v0
	v_mul_f32_e32 v10, 0xbfb8aa3b, v19
	v_lshlrev_b32_e32 v20, 16, v1
	v_lshlrev_b32_e32 v18, 16, v0
	v_exp_f32_e32 v10, v10
	v_and_b32_e32 v21, 0xffff0000, v1
	v_mul_f32_e32 v1, 0xbfb8aa3b, v20
	v_mul_f32_e32 v0, 0xbfb8aa3b, v18
	v_exp_f32_e32 v29, v1
	v_mul_f32_e32 v1, 0xbfb8aa3b, v21
	v_pk_mul_f32 v[16:17], v[16:17], v[34:35]
	v_exp_f32_e32 v0, v0
	v_exp_f32_e32 v35, v1
	v_add_f32_e32 v10, 1.0, v10
	v_rcp_f32_e32 v1, v10
	v_add_f32_e32 v10, 1.0, v29
	v_add_f32_e32 v0, 1.0, v0
	v_rcp_f32_e32 v34, v10
	v_add_f32_e32 v10, 1.0, v35
	v_rcp_f32_e32 v0, v0
	v_rcp_f32_e32 v35, v10
	v_pk_mul_f32 v[32:33], v[14:15], v[14:15]
	v_pk_mul_f32 v[48:49], v[16:17], v[16:17]
	v_pk_mul_f32 v[0:1], v[0:1], v[18:19]
	v_pk_mul_f32 v[18:19], v[34:35], v[20:21]
	v_and_b32_e32 v21, 0xffff0000, v2
	v_pk_mul_f32 v[0:1], v[0:1], v[36:37]
	v_mul_f32_e32 v10, 0xbfb8aa3b, v21
	v_lshlrev_b32_e32 v36, 16, v3
	v_lshlrev_b32_e32 v20, 16, v2
	v_exp_f32_e32 v10, v10
	v_and_b32_e32 v37, 0xffff0000, v3
	v_mul_f32_e32 v3, 0xbfb8aa3b, v36
	v_mul_f32_e32 v2, 0xbfb8aa3b, v20
	v_exp_f32_e32 v29, v3
	v_mul_f32_e32 v3, 0xbfb8aa3b, v37
	v_pk_mul_f32 v[18:19], v[18:19], v[38:39]
	v_exp_f32_e32 v2, v2
	v_exp_f32_e32 v39, v3
	v_add_f32_e32 v10, 1.0, v10
	v_rcp_f32_e32 v3, v10
	v_add_f32_e32 v10, 1.0, v29
	v_add_f32_e32 v2, 1.0, v2
	v_rcp_f32_e32 v38, v10
	v_add_f32_e32 v10, 1.0, v39
	v_rcp_f32_e32 v2, v2
	v_rcp_f32_e32 v39, v10
	v_pk_mul_f32 v[46:47], v[6:7], v[6:7]
	v_add_f32_e32 v10, v48, v49
	v_add_f32_e32 v29, v32, v33
	v_add_f32_e32 v10, v29, v10
	v_add_f32_e32 v29, v46, v47
	v_add_f32_e32 v32, v44, v45
	v_pk_mul_f32 v[34:35], v[0:1], v[0:1]
	v_pk_mul_f32 v[50:51], v[18:19], v[18:19]
	v_pk_mul_f32 v[2:3], v[2:3], v[20:21]
	v_pk_mul_f32 v[20:21], v[38:39], v[36:37]
	v_add_f32_e32 v29, v32, v29
	v_pk_mul_f32 v[2:3], v[2:3], v[40:41]
	v_pk_mul_f32 v[20:21], v[20:21], v[42:43]
	v_add_f32_e32 v10, v29, v10
	v_add_f32_e32 v29, v50, v51
	v_add_f32_e32 v32, v34, v35
	v_pk_mul_f32 v[36:37], v[2:3], v[2:3]
	v_pk_mul_f32 v[38:39], v[20:21], v[20:21]
	v_add_f32_e32 v29, v32, v29
	v_add_f32_e32 v10, v10, v29
	v_add_f32_e32 v29, v38, v39
	v_add_f32_e32 v32, v36, v37
	v_add_f32_e32 v29, v32, v29
	v_add_f32_e32 v10, v10, v29
	ds_bpermute_b32 v29, v22, v10
	s_waitcnt lgkmcnt(0)
	v_add_f32_e32 v29, v10, v29
	ds_bpermute_b32 v32, v23, v29
	v_lshlrev_b32_e32 v10, 3, v27
	s_and_saveexec_b64 s[12:13], s[2:3]
	s_cbranch_execz .LBB0_931
	s_lshl_b32 s2, s20, 2
	v_add3_u32 v26, v24, v10, s2
	s_waitcnt lgkmcnt(0)
	v_add_f32_e32 v27, v29, v32
	ds_write_b32 v26, v27
.LBB0_931:
	s_or_b64 exec, exec, s[12:13]
	s_waitcnt lgkmcnt(0)
	s_barrier
	s_and_saveexec_b64 s[2:3], vcc
	s_cbranch_execz .LBB0_922
	s_nop 0
	s_nop 0
	s_nop 0
	s_nop 0
	s_nop 0
	v_or_b32_e32 v36, s10, v28
	v_ashrrev_i32_e32 v37, 31, v36
	v_add_u32_e32 v10, v24, v10
	v_lshlrev_b64 v[12:13], 11, v[12:13]
	ds_read2_b32 v[40:41], v10 offset1:1
	v_lshl_add_u64 v[12:13], s[4:5], 0, v[12:13]
	s_waitcnt lgkmcnt(0)
	v_add_f32_e32 v10, v40, v41
	v_fmamk_f32 v10, v10, 0x3c000000, v25
	v_mul_f32_e32 v40, 0x4b800000, v10
	v_cmp_gt_f32_e32 vcc, s19, v10
	s_nop 1
	v_cndmask_b32_e32 v10, v10, v40, vcc
	v_rsq_f32_e32 v10, v10
	v_lshl_add_u64 v[40:41], v[12:13], 0, s[8:9]
	v_lshl_add_u64 v[12:13], v[36:37], 1, v[40:41]
	v_mul_f32_e32 v37, 0x45800000, v10
	v_cndmask_b32_e32 v10, v10, v37, vcc
	v_pk_mul_f32 v[4:5], v[4:5], v[10:11] op_sel_hi:[1,0]
	v_pk_mul_f32 v[6:7], v[6:7], v[10:11] op_sel_hi:[1,0]
	v_pk_mul_f32 v[14:15], v[14:15], v[10:11] op_sel_hi:[1,0]
	v_pk_mul_f32 v[16:17], v[16:17], v[10:11] op_sel_hi:[1,0]
	v_pk_mul_f32 v[0:1], v[0:1], v[10:11] op_sel_hi:[1,0]
	v_pk_mul_f32 v[18:19], v[18:19], v[10:11] op_sel_hi:[1,0]
	v_pk_mul_f32 v[2:3], v[2:3], v[10:11] op_sel_hi:[1,0]
	v_pk_mul_f32 v[20:21], v[20:21], v[10:11] op_sel_hi:[1,0]
	v_pk_mul_f32 v[4:5], v[142:143], v[4:5]
	v_pk_mul_f32 v[6:7], v[144:145], v[6:7]
	v_pk_mul_f32 v[14:15], v[146:147], v[14:15]
	v_pk_mul_f32 v[16:17], v[148:149], v[16:17]
	v_cvt_pk_bf16_f32 v4, v4, v5
	v_cvt_pk_bf16_f32 v5, v6, v7
	v_cvt_pk_bf16_f32 v6, v14, v15
	v_cvt_pk_bf16_f32 v7, v16, v17
	global_store_dwordx4 v[12:13], v[4:7], off
	s_nop 0
	v_or_b32_e32 v16, 32, v36
	v_ashrrev_i32_e32 v17, 31, v16
	v_pk_mul_f32 v[0:1], v[150:151], v[0:1]
	v_pk_mul_f32 v[4:5], v[152:153], v[18:19]
	v_pk_mul_f32 v[2:3], v[154:155], v[2:3]
	v_pk_mul_f32 v[6:7], v[156:157], v[20:21]
	v_cvt_pk_bf16_f32 v0, v0, v1
	v_cvt_pk_bf16_f32 v1, v4, v5
	v_cvt_pk_bf16_f32 v2, v2, v3
	v_cvt_pk_bf16_f32 v3, v6, v7
	v_lshl_add_u64 v[4:5], v[16:17], 1, v[40:41]
	global_store_dwordx4 v[4:5], v[0:3], off
	s_branch .LBB0_922

.LBB0_2415:
	s_cmp_lt_i32 s88, 14
	s_cselect_b64 s[0:1], -1, 0
	s_cmp_gt_i32 s89, 13
	s_cselect_b64 s[2:3], -1, 0
	s_and_b64 s[0:1], s[0:1], s[2:3]
	s_andn2_b64 vcc, exec, s[0:1]
	s_cbranch_vccnz .LBB0_2488
	v_readlane_b32 s0, v254, 0
	s_waitcnt vmcnt(0)
	v_mbcnt_lo_u32_b32 v0, -1, 0
	s_andn2_b32 s0, s0, 63
	v_mbcnt_hi_u32_b32 v32, -1, v0
	v_or_b32_e32 v30, s0, v32
	v_mov_b32_e32 v31, 0
	s_mov_b32 s22, s90
	v_readlane_b32 s2, v254, 3
	s_mov_b64 s[0:1], s[92:93]
	v_readlane_b32 s23, v254, 4
	s_waitcnt lgkmcnt(0)
	s_load_dwordx2 s[4:5], s[0:1], 0xe8
	s_load_dwordx2 s[38:39], s[0:1], 0x68
	s_load_dwordx2 s[40:41], s[0:1], 0x98
	s_mov_b32 s7, 0
	v_mov_b32_e32 v25, 0
	s_cmpk_gt_i32 s23, 0x3ff
	v_xor_b32_e32 v34, 16, v32
	v_and_b32_e32 v35, 64, v32
	v_xor_b32_e32 v33, 32, v32
	s_cbranch_scc1 .LBB0_2429
	s_waitcnt lgkmcnt(0)
	s_add_u32 s24, s4, 0x10000000
	s_addc_u32 s25, s5, 0
	v_add_u32_e32 v0, 64, v35
	s_add_u32 s26, s4, 0x16100000
	v_cmp_lt_i32_e32 vcc, v34, v0
	s_addc_u32 s27, s5, 0
	s_add_u32 s8, s4, 0xb00000
	v_cndmask_b32_e32 v1, v32, v34, vcc
	v_cmp_lt_i32_e32 vcc, v33, v0
	s_addc_u32 s9, s5, 0
	v_lshlrev_b32_e32 v36, 2, v1
	v_cndmask_b32_e32 v0, v32, v33, vcc
	v_lshlrev_b32_e32 v37, 2, v0
	s_mov_b64 s[10:11], 0x10000
	s_mov_b64 s[12:13], 0x10400
	s_mov_b64 s[14:15], 0x14000
	s_movk_i32 s28, 0x1c00
	v_mov_b64_e32 v[26:27], s[4:5]
	s_mov_b64 s[16:17], 0x2e00c00
	s_mov_b32 s29, 0x2e00000
	s_mov_b32 s30, 0xc000
	v_mov_b32_e32 v38, 0x358637bd
	s_mov_b32 s31, 0x800000
	s_mov_b32 s33, s23
	s_branch .LBB0_2419

.LBB0_2438:
	s_or_b64 exec, exec, s[10:11]
	s_nop 0
	s_lshl_b32 s10, s13, 6
	v_lshrrev_b32_e32 v2, 1, v14
	v_mad_i64_i32 v[0:1], s[2:3], v12, s17, v[8:9]
	s_ashr_i32 s11, s10, 31
	v_and_b32_e32 v28, 24, v2
	v_bitop3_b32 v20, v10, v16, s16 bitop3:0x6c
	v_bitop3_b32 v19, v10, v18, s16 bitop3:0x6c
	v_lshl_add_u64 v[0:1], s[10:11], 1, v[0:1]
	v_lshlrev_b32_e32 v10, 1, v28
	v_lshl_add_u64 v[0:1], v[0:1], 0, v[10:11]
	v_add_co_u32_e64 v48, s[2:3], s18, v0
	s_nop 0
	v_addc_co_u32_e64 v49, s[2:3], 0, v1, s[2:3]
	v_lshl_add_u64 v[42:43], v[0:1], 0, s[6:7]
	v_or_b32_e32 v158, s10, v28
	v_lshlrev_b32_e32 v158, 2, v158
	global_load_dwordx4 v[142:145], v158, s[40:41] offset:1024
	global_load_dwordx4 v[146:149], v158, s[40:41] offset:1040
	global_load_dwordx4 v[150:153], v158, s[40:41] offset:1152
	global_load_dwordx4 v[154:157], v158, s[40:41] offset:1168
	global_load_dwordx4 v[44:47], v[48:49], off offset:1536
	global_load_dwordx4 v[0:3], v[42:43], off offset:64
	v_lshl_add_u32 v4, s20, 14, v31
	v_lshlrev_b32_e32 v15, 1, v15
	v_and_b32_e32 v14, 3, v14
	v_lshl_add_u32 v10, v27, 8, v4
	v_and_or_b32 v15, v15, 24, v14
	s_waitcnt vmcnt(0) lgkmcnt(0)
	s_barrier
	v_lshlrev_b32_e32 v36, 16, v118
	v_and_b32_e32 v37, 0xffff0000, v118
	v_lshlrev_b32_e32 v32, 16, v116
	v_and_b32_e32 v33, 0xffff0000, v116
	v_lshlrev_b32_e32 v34, 16, v117
	v_and_b32_e32 v35, 0xffff0000, v117
	v_lshlrev_b32_e32 v38, 16, v119
	v_and_b32_e32 v39, 0xffff0000, v119
	v_lshlrev_b32_e32 v40, 16, v120
	v_and_b32_e32 v41, 0xffff0000, v120
	v_lshlrev_b32_e32 v29, 4, v14
	v_add_u32_e32 v14, v10, v20
	v_lshl_add_u32 v64, v15, 8, v4
	v_xad_u32 v20, v29, v16, v64
	ds_read_b128 v[48:51], v14 offset:32768
	ds_read_b128 v[52:55], v20
	v_lshlrev_b32_e32 v42, 16, v121
	v_and_b32_e32 v43, 0xffff0000, v121
	v_or_b32_e32 v5, 4, v15
	v_lshlrev_b32_e32 v14, 4, v5
	v_and_b32_e32 v65, 0x70, v14
	v_lshl_add_u32 v66, v5, 8, v4
	v_xad_u32 v5, v65, v16, v66
	ds_read_b128 v[56:59], v5
	s_waitcnt lgkmcnt(0)
	v_mfma_f32_16x16x32_bf16 v[32:35], v[52:55], v[48:51], v[32:35]
	ds_read_b128 v[52:55], v20 offset:8192
	v_or_b32_e32 v5, 36, v15
	v_lshlrev_b32_e32 v14, 4, v5
	v_and_b32_e32 v67, 0x70, v14
	v_lshl_add_u32 v68, v5, 8, v4
	v_xad_u32 v4, v67, v16, v68
	ds_read_b128 v[60:63], v4
	v_add_u32_e32 v14, v10, v19
	v_and_b32_e32 v5, 0xffff0000, v122
	s_waitcnt lgkmcnt(1)
	v_mfma_f32_16x16x32_bf16 v[40:43], v[52:55], v[48:51], v[40:43]
	ds_read_b128 v[52:55], v14 offset:32768
	v_lshlrev_b32_e32 v4, 16, v122
	v_lshlrev_b32_e32 v6, 16, v123
	v_and_b32_e32 v7, 0xffff0000, v123
	v_xad_u32 v14, v29, v18, v64
	v_mfma_f32_16x16x32_bf16 v[36:39], v[56:59], v[48:51], v[36:39]
	v_cmp_gt_u32_e64 s[2:3], 16, v26
	s_waitcnt lgkmcnt(1)
	v_mfma_f32_16x16x32_bf16 v[4:7], v[60:63], v[48:51], v[4:7]
	ds_read_b128 v[48:51], v14
	ds_read_b128 v[56:59], v14 offset:8192
	v_xad_u32 v14, v65, v18, v66
	s_waitcnt lgkmcnt(1)
	v_mfma_f32_16x16x32_bf16 v[32:35], v[48:51], v[52:55], v[32:35]
	ds_read_b128 v[48:51], v14
	v_xad_u32 v14, v67, v18, v68
	ds_read_b128 v[18:21], v14
	v_or_b32_e32 v14, 0x80, v16
	v_xad_u32 v15, v29, v14, v64
	s_waitcnt lgkmcnt(1)
	v_mfma_f32_16x16x32_bf16 v[36:39], v[48:51], v[52:55], v[36:39]
	ds_read_b128 v[48:51], v15
	s_waitcnt lgkmcnt(1)
	v_mfma_f32_16x16x32_bf16 v[4:7], v[18:21], v[52:55], v[4:7]
	v_xad_u32 v18, v17, v14, v10
	ds_read_b128 v[18:21], v18 offset:32768
	s_waitcnt lgkmcnt(0)
	v_mfma_f32_16x16x32_bf16 v[32:35], v[48:51], v[18:21], v[32:35]
	v_xad_u32 v48, v65, v14, v66
	v_xad_u32 v14, v67, v14, v68
	v_mfma_f32_16x16x32_bf16 v[40:43], v[56:59], v[52:55], v[40:43]
	ds_read_b128 v[48:51], v48
	ds_read_b128 v[52:55], v15 offset:8192
	s_waitcnt vmcnt(1)
	v_lshlrev_b32_e32 v56, 16, v44
	s_waitcnt lgkmcnt(1)
	v_mfma_f32_16x16x32_bf16 v[36:39], v[48:51], v[18:21], v[36:39]
	ds_read_b128 v[48:51], v14
	v_and_b32_e32 v57, 0xffff0000, v44
	s_waitcnt lgkmcnt(1)
	v_mfma_f32_16x16x32_bf16 v[40:43], v[52:55], v[18:21], v[40:43]
	v_or_b32_e32 v52, 0xc0, v16
	v_xad_u32 v10, v17, v52, v10
	ds_read_b128 v[14:17], v10 offset:32768
	v_xad_u32 v10, v29, v52, v64
	s_waitcnt lgkmcnt(1)
	v_mfma_f32_16x16x32_bf16 v[4:7], v[48:51], v[18:21], v[4:7]
	ds_read_b128 v[18:21], v10
	ds_read_b128 v[48:51], v10 offset:8192
	v_xad_u32 v10, v65, v52, v66
	v_mul_f32_e32 v29, 0xbfb8aa3b, v57
	s_waitcnt lgkmcnt(1)
	v_mfma_f32_16x16x32_bf16 v[18:21], v[18:21], v[14:17], v[32:35]
	v_exp_f32_e32 v29, v29
	s_nop 1
	ds_read_b128 v[32:35], v10
	v_xad_u32 v10, v67, v52, v68
	ds_read_b128 v[52:55], v10
	v_mul_f32_e32 v10, 0xbfb8aa3b, v56
	v_exp_f32_e32 v10, v10
	s_waitcnt lgkmcnt(1)
	v_mfma_f32_16x16x32_bf16 v[32:35], v[32:35], v[14:17], v[36:39]
	v_add_f32_e32 v10, 1.0, v10
	v_rcp_f32_e32 v44, v10
	v_add_f32_e32 v10, 1.0, v29
	v_mfma_f32_16x16x32_bf16 v[36:39], v[48:51], v[14:17], v[40:43]
	v_lshlrev_b32_e32 v48, 16, v45
	v_and_b32_e32 v49, 0xffff0000, v45
	v_mul_f32_e32 v29, 0xbfb8aa3b, v48
	v_exp_f32_e32 v29, v29
	v_mul_f32_e32 v40, 0xbfb8aa3b, v49
	v_exp_f32_e32 v40, v40
	v_rcp_f32_e32 v45, v10
	v_add_f32_e32 v10, 1.0, v29
	v_rcp_f32_e32 v50, v10
	v_add_f32_e32 v10, 1.0, v40
	s_waitcnt lgkmcnt(0)
	v_mfma_f32_16x16x32_bf16 v[40:43], v[52:55], v[14:17], v[4:7]
	v_lshlrev_b32_e32 v14, 16, v46
	v_rcp_f32_e32 v51, v10
	v_and_b32_e32 v15, 0xffff0000, v46
	v_mul_f32_e32 v10, 0xbfb8aa3b, v14
	v_exp_f32_e32 v10, v10
	v_mul_f32_e32 v16, 0xbfb8aa3b, v15
	v_exp_f32_e32 v17, v16
	v_pk_mul_f32 v[4:5], v[44:45], v[56:57]
	v_add_f32_e32 v10, 1.0, v10
	v_pk_mul_f32 v[4:5], v[4:5], v[18:19]
	v_lshlrev_b32_e32 v18, 16, v47
	v_pk_mul_f32 v[6:7], v[50:51], v[48:49]
	v_rcp_f32_e32 v16, v10
	v_add_f32_e32 v10, 1.0, v17
	v_and_b32_e32 v19, 0xffff0000, v47
	v_mul_f32_e32 v17, 0xbfb8aa3b, v18
	v_pk_mul_f32 v[6:7], v[6:7], v[20:21]
	v_exp_f32_e32 v20, v17
	v_mul_f32_e32 v17, 0xbfb8aa3b, v19
	v_exp_f32_e32 v21, v17
	v_rcp_f32_e32 v17, v10
	v_add_f32_e32 v10, 1.0, v20
	v_rcp_f32_e32 v20, v10
	v_add_f32_e32 v10, 1.0, v21
	v_rcp_f32_e32 v21, v10
	v_pk_mul_f32 v[14:15], v[16:17], v[14:15]
	v_pk_mul_f32 v[44:45], v[4:5], v[4:5]
	v_pk_mul_f32 v[14:15], v[14:15], v[32:33]
	v_pk_mul_f32 v[16:17], v[20:21], v[18:19]
	s_waitcnt vmcnt(0)
	v_and_b32_e32 v19, 0xffff0000, v0
	v_mul_f32_e32 v10, 0xbfb8aa3b, v19
	v_lshlrev_b32_e32 v20, 16, v1
	v_lshlrev_b32_e32 v18, 16, v0
	v_exp_f32_e32 v10, v10
	v_and_b32_e32 v21, 0xffff0000, v1
	v_mul_f32_e32 v1, 0xbfb8aa3b, v20
	v_mul_f32_e32 v0, 0xbfb8aa3b, v18
	v_exp_f32_e32 v29, v1
	v_mul_f32_e32 v1, 0xbfb8aa3b, v21
	v_pk_mul_f32 v[16:17], v[16:17], v[34:35]
	v_exp_f32_e32 v0, v0
	v_exp_f32_e32 v35, v1
	v_add_f32_e32 v10, 1.0, v10
	v_rcp_f32_e32 v1, v10
	v_add_f32_e32 v10, 1.0, v29
	v_add_f32_e32 v0, 1.0, v0
	v_rcp_f32_e32 v34, v10
	v_add_f32_e32 v10, 1.0, v35
	v_rcp_f32_e32 v0, v0
	v_rcp_f32_e32 v35, v10
	v_pk_mul_f32 v[32:33], v[14:15], v[14:15]
	v_pk_mul_f32 v[48:49], v[16:17], v[16:17]
	v_pk_mul_f32 v[0:1], v[0:1], v[18:19]
	v_pk_mul_f32 v[18:19], v[34:35], v[20:21]
	v_and_b32_e32 v21, 0xffff0000, v2
	v_pk_mul_f32 v[0:1], v[0:1], v[36:37]
	v_mul_f32_e32 v10, 0xbfb8aa3b, v21
	v_lshlrev_b32_e32 v36, 16, v3
	v_lshlrev_b32_e32 v20, 16, v2
	v_exp_f32_e32 v10, v10
	v_and_b32_e32 v37, 0xffff0000, v3
	v_mul_f32_e32 v3, 0xbfb8aa3b, v36
	v_mul_f32_e32 v2, 0xbfb8aa3b, v20
	v_exp_f32_e32 v29, v3
	v_mul_f32_e32 v3, 0xbfb8aa3b, v37
	v_pk_mul_f32 v[18:19], v[18:19], v[38:39]
	v_exp_f32_e32 v2, v2
	v_exp_f32_e32 v39, v3
	v_add_f32_e32 v10, 1.0, v10
	v_rcp_f32_e32 v3, v10
	v_add_f32_e32 v10, 1.0, v29
	v_add_f32_e32 v2, 1.0, v2
	v_rcp_f32_e32 v38, v10
	v_add_f32_e32 v10, 1.0, v39
	v_rcp_f32_e32 v2, v2
	v_rcp_f32_e32 v39, v10
	v_pk_mul_f32 v[46:47], v[6:7], v[6:7]
	v_add_f32_e32 v10, v48, v49
	v_add_f32_e32 v29, v32, v33
	v_add_f32_e32 v10, v29, v10
	v_add_f32_e32 v29, v46, v47
	v_add_f32_e32 v32, v44, v45
	v_pk_mul_f32 v[34:35], v[0:1], v[0:1]
	v_pk_mul_f32 v[50:51], v[18:19], v[18:19]
	v_pk_mul_f32 v[2:3], v[2:3], v[20:21]
	v_pk_mul_f32 v[20:21], v[38:39], v[36:37]
	v_add_f32_e32 v29, v32, v29
	v_pk_mul_f32 v[2:3], v[2:3], v[40:41]
	v_pk_mul_f32 v[20:21], v[20:21], v[42:43]
	v_add_f32_e32 v10, v29, v10
	v_add_f32_e32 v29, v50, v51
	v_add_f32_e32 v32, v34, v35
	v_pk_mul_f32 v[36:37], v[2:3], v[2:3]
	v_pk_mul_f32 v[38:39], v[20:21], v[20:21]
	v_add_f32_e32 v29, v32, v29
	v_add_f32_e32 v10, v10, v29
	v_add_f32_e32 v29, v38, v39
	v_add_f32_e32 v32, v36, v37
	v_add_f32_e32 v29, v32, v29
	v_add_f32_e32 v10, v10, v29
	ds_bpermute_b32 v29, v22, v10
	s_waitcnt lgkmcnt(0)
	v_add_f32_e32 v29, v10, v29
	ds_bpermute_b32 v32, v23, v29
	v_lshlrev_b32_e32 v10, 3, v27
	s_and_saveexec_b64 s[12:13], s[2:3]
	s_cbranch_execz .LBB0_2440
	s_lshl_b32 s2, s20, 2
	v_add3_u32 v26, v24, v10, s2
	s_waitcnt lgkmcnt(0)
	v_add_f32_e32 v27, v29, v32
	ds_write_b32 v26, v27
